# nt hint on the rwkv post-phase streaming row loads (dead-after-read operands)
# speedup vs baseline: 1.0069x; 1.0001x over previous
; DEV void post_phase(const Params& p, int l, int nrows) {
;     ...
;   auto gl = [&](int rw) {
;     q_ysf = *(const u32x4*)(YSF + (size_t)rw * 512 + c0); q_ysb = *(const u32x4*)(YSB + (size_t)rw * 512 + c0);
;     q_r = *(const u32x4*)(ZRS + (size_t)rw * 1536 + c0); q_k = *(const u32x4*)(ZRS + (size_t)rw * 1536 + 512 + c0);
;     q_v = *(const u32x4*)(ZRS + (size_t)rw * 1536 + 1024 + c0);
;     q_af = *(const u32x4*)(AF + (size_t)rw * 512 + c0); q_ab = *(const u32x4*)(AB + (size_t)rw * 512 + c0);
;     q_g = *(const u32x4*)(G + (size_t)rw * 512 + c0);
;   };
.LBB0_167:
	v_add_u32_e32 v98, s60, v98
	v_cmp_le_i32_e64 s[0:1], s96, v98
	v_cmp_gt_i32_e32 vcc, s96, v98
	s_or_b64 s[36:37], s[0:1], s[36:37]
	s_and_saveexec_b64 s[0:1], vcc
	s_cbranch_execz .LBB0_166
	v_lshl_add_u64 v[64:65], v[104:105], 0, v[96:97]
	v_add_co_u32_e32 v32, vcc, 0xcc00000, v64
	v_lshl_add_u64 v[40:41], v[102:103], 0, v[96:97]
	s_nop 0
	v_addc_co_u32_e32 v33, vcc, 0, v65, vcc
	v_add_co_u32_e32 v36, vcc, 0x15400000, v64
	s_nop 1
	v_addc_co_u32_e32 v37, vcc, 0, v65, vcc
	v_add_co_u32_e32 v44, vcc, 0xee00000, v40
	global_load_dwordx4 v[32:35], v[32:33], off nt
	s_nop 0
	global_load_dwordx4 v[36:39], v[36:37], off nt
	v_addc_co_u32_e32 v45, vcc, 0, v41, vcc
	v_add_co_u32_e32 v52, vcc, 0x8800000, v64
	global_load_dwordx4 v[48:51], v[44:45], off nt
	global_load_dwordx4 v[40:43], v[44:45], off offset:1024 nt
	s_nop 0
	global_load_dwordx4 v[44:47], v[44:45], off offset:2048 nt
	v_addc_co_u32_e32 v53, vcc, 0, v65, vcc
	v_add_co_u32_e32 v56, vcc, 0xaa00000, v64
	s_nop 1
	v_addc_co_u32_e32 v57, vcc, 0, v65, vcc
	v_add_co_u32_e32 v64, vcc, 0x4400000, v64
	global_load_dwordx4 v[52:55], v[52:53], off nt
	s_nop 0
	global_load_dwordx4 v[56:59], v[56:57], off nt
	v_addc_co_u32_e32 v65, vcc, 0, v65, vcc
	global_load_dwordx4 v[64:67], v[64:65], off nt
	s_branch .LBB0_166
